# rot epilogue preload + per-group GEMM phase start stagger (4 groups x ~2us)
# baseline (speedup 1.0000x reference)
.LBB0_249:
	s_cmp_lt_i32 s86, 2
	s_cselect_b64 s[2:3], -1, 0
	s_and_b64 s[2:3], s[2:3], s[0:1]
	s_andn2_b64 vcc, exec, s[2:3]
	s_cbranch_vccnz .LBB0_266
	s_bfe_u32 s0, s81, 0x20006
	s_cmp_eq_u32 s0, 0
	s_cbranch_scc1 .Lstg1_done
.Lstg1_loop:
	s_sleep 70
	s_add_i32 s0, s0, -1
	s_cmp_lg_u32 s0, 0
	s_cbranch_scc1 .Lstg1_loop
.Lstg1_done:
	s_cmpk_gt_i32 s81, 0x15ff
	v_readfirstlane_b32 s1, v182
	s_cbranch_scc1 .LBB0_266
	v_lshrrev_b32_e32 v2, 1, v182
	v_and_b32_e32 v11, 24, v2
	v_lshrrev_b32_e32 v2, 5, v182
	v_and_b32_e32 v2, 4, v2
	v_bfe_u32 v3, v182, 2, 2
	s_add_u32 s28, s84, 0x4000000
	v_lshlrev_b32_e32 v0, 4, v182
	v_and_b32_e32 v1, 32, v182
	v_bfe_u32 v10, v182, 2, 4
	v_or3_b32 v2, v2, v3, v11
	v_lshrrev_b32_e32 v3, 3, v182
	s_movk_i32 s0, 0x70
	s_addc_u32 s29, s85, 0
	v_bitop3_b32 v8, v0, v1, 48 bitop3:0x6c
	v_and_b32_e32 v9, 64, v182
	v_and_or_b32 v4, v3, s0, v10
	s_movk_i32 s0, 0x60
	v_add_u32_e32 v12, 0x2000, v0
	s_add_u32 s30, s84, 0xa00000
	v_or_b32_e32 v1, v8, v9
	v_and_or_b32 v3, v3, s0, v2
	v_lshrrev_b32_e32 v0, 7, v12
	s_movk_i32 s0, 0xf0
	s_addc_u32 s31, s85, 0
	v_lshl_or_b32 v130, v3, 11, v1
	v_and_or_b32 v3, v0, s0, v10
	s_movk_i32 s0, 0xe0
	s_ashr_i32 s33, s81, 31
	v_and_or_b32 v0, v0, s0, v2
	s_lshr_b32 s0, s33, 29
	s_add_i32 s0, s81, s0
	s_lshr_b32 s8, s1, 6
	s_ashr_i32 s4, s0, 3
	s_and_b32 s0, s0, -8
	s_lshr_b32 s10, s1, 8
	s_lshl_b32 s34, s8, 10
	s_sub_i32 s0, s81, s0
	s_cmp_lt_i32 s0, 0
	s_movk_i32 s35, 0x2c1
	s_cselect_b32 s5, s35, 0x2c0
	s_mul_i32 s0, s0, s5
	s_add_i32 s0, s0, s4
	s_mul_hi_i32 s4, s0, 0x2e8ba2e9
	s_lshr_b32 s5, s4, 31
	s_ashr_i32 s4, s4, 5
	s_add_i32 s4, s4, s5
	s_lshl_b32 s5, s4, 3
	s_mulk_i32 s4, 0xb0
	s_sub_i32 s4, s0, s4
	s_bfe_u32 s0, s4, 0x3001c
	s_add_i32 s6, s4, s0
	s_sext_i32_i16 s0, s6
	s_and_b32 s6, s6, 0xfff8
	s_sub_i32 s4, s4, s6
	s_sext_i32_i16 s4, s4
	s_lshr_b32 s0, s0, 3
	s_add_i32 s20, s5, s4
	s_ashr_i32 s21, s20, 31
	s_bfe_i64 s[6:7], s[0:1], 0x100000
	s_lshl_b64 s[4:5], s[20:21], 19
	s_lshl_b64 s[6:7], s[6:7], 19
	s_add_u32 s24, s30, s6
	s_addc_u32 s25, s31, s7
	s_add_i32 s21, s34, 0
	s_add_i32 m0, s21, 0x10000
	v_lshl_or_b32 v134, v0, 11, v1
	global_load_lds_dwordx4 v130, s[24:25]
	s_add_i32 m0, s21, 0x12000
	s_add_u32 s6, s24, 0x40000
	global_load_lds_dwordx4 v134, s[24:25]
	s_addc_u32 s7, s25, 0
	s_add_i32 m0, s21, 0x14000
	v_lshl_or_b32 v128, v4, 11, v1
	global_load_lds_dwordx4 v130, s[6:7]
	s_add_i32 m0, s21, 0x16000
	s_add_u32 s22, s28, s4
	s_addc_u32 s23, s29, s5
	s_add_i32 s36, s21, 0x2000
	global_load_lds_dwordx4 v134, s[6:7]
	s_mov_b32 m0, s21
	s_add_u32 s4, s22, 0x40000
	v_lshl_or_b32 v132, v3, 11, v1
	global_load_lds_dwordx4 v128, s[22:23]
	s_mov_b32 m0, s36
	s_addc_u32 s5, s23, 0
	s_add_i32 s37, s21, 0x4000
	global_load_lds_dwordx4 v132, s[22:23]
	s_mov_b32 m0, s37
	s_add_i32 s38, s21, 0x6000
	global_load_lds_dwordx4 v128, s[4:5]
	s_mov_b32 m0, s38
	v_mov_b32_e32 v131, 0
	global_load_lds_dwordx4 v132, s[4:5]
	v_mov_b32_e32 v135, v131
	v_mov_b32_e32 v129, v131
	v_mov_b32_e32 v133, v131
	s_cmp_eq_u32 s10, 1
	s_mov_b32 s39, 0
	v_lshl_add_u64 v[6:7], s[24:25], 0, v[130:131]
	v_lshl_add_u64 v[4:5], s[24:25], 0, v[134:135]
	v_lshl_add_u64 v[0:1], s[22:23], 0, v[128:129]
	s_cselect_b64 s[4:5], -1, 0
	s_cmp_lg_u32 s10, 1
	v_lshl_add_u64 v[2:3], s[22:23], 0, v[132:133]
	s_cbranch_scc1 .LBB0_253
	s_barrier

.LBB0_320:
	s_cmp_lt_i32 s86, 3
	s_cselect_b64 s[2:3], -1, 0
	s_and_b64 s[2:3], s[2:3], s[0:1]
	s_andn2_b64 vcc, exec, s[2:3]
	s_cbranch_vccnz .LBB0_345
	s_bfe_u32 s0, s81, 0x20006
	s_cmp_eq_u32 s0, 0
	s_cbranch_scc1 .Lstg2_done

.Lstg2_done:
	s_cmpk_gt_i32 s81, 0x3ff
	v_readfirstlane_b32 s0, v182
	s_cbranch_scc1 .LBB0_345
	s_add_u32 s30, s84, 0x14000000
	s_addc_u32 s31, s85, 0
	v_lshrrev_b32_e32 v3, 1, v182
	s_add_u32 s33, s84, 0x1500000
	v_and_b32_e32 v10, 24, v3
	v_lshrrev_b32_e32 v3, 5, v182
	s_addc_u32 s34, s85, 0
	v_and_b32_e32 v3, 4, v3
	v_bfe_u32 v4, v182, 2, 2
	s_ashr_i32 s35, s81, 31
	v_lshlrev_b32_e32 v0, 4, v182
	v_and_b32_e32 v1, 32, v182
	v_bfe_u32 v2, v182, 2, 4
	v_or3_b32 v3, v3, v4, v10
	v_lshrrev_b32_e32 v4, 3, v182
	s_movk_i32 s1, 0x70
	s_lshr_b32 s4, s35, 29
	v_bitop3_b32 v8, v0, v1, 48 bitop3:0x6c
	v_and_or_b32 v5, v4, s1, v2
	s_movk_i32 s1, 0x60
	v_add_u32_e32 v0, 0x2000, v0
	s_add_i32 s4, s81, s4
	v_and_or_b32 v4, v4, s1, v3
	v_lshrrev_b32_e32 v0, 7, v0
	s_movk_i32 s1, 0xf0
	s_ashr_i32 s6, s4, 3
	s_and_b32 s4, s4, -8
	v_and_or_b32 v2, v0, s1, v2
	s_movk_i32 s1, 0xe0
	s_lshr_b32 s5, s0, 6
	s_sub_i32 s4, s81, s4
	v_and_or_b32 v0, v0, s1, v3
	s_lshr_b32 s1, s0, 8
	s_lshl_b32 s36, s5, 10
	s_lshl_b32 s8, s4, 7
	s_mul_i32 s7, s4, 0x81
	s_cmp_lt_i32 s4, 0
	s_cselect_b32 s4, s7, s8
	s_add_i32 s4, s4, s6
	s_ashr_i32 s6, s4, 31
	s_lshr_b32 s6, s6, 27
	s_add_i32 s6, s4, s6
	s_ashr_i32 s7, s6, 5
	s_and_b32 s6, s6, 0xffe0
	s_sub_i32 s6, s4, s6
	s_bfe_i32 s4, s6, 0x80000
	s_bfe_u32 s4, s4, 0x3000c
	s_add_i32 s8, s6, s4
	s_bfe_i32 s4, s8, 0x80000
	s_and_b32 s8, s8, 0xf8
	s_sub_i32 s6, s6, s8
	s_lshl_b32 s7, s7, 3
	s_sext_i32_i16 s9, s4
	s_sext_i32_i8 s6, s6
	v_and_b32_e32 v9, 64, v182
	s_add_i32 s51, s7, s6
	s_ashr_i32 s6, s9, 3
	v_or_b32_e32 v1, v8, v9
	s_lshr_b32 s4, s9, 3
	s_mul_hi_i32 s7, s6, 0x160000
	s_mul_i32 s6, s6, 0x160000
	v_lshrrev_b32_e32 v1, 1, v1
	v_mul_u32_u24_e32 v4, 0xb00, v4
	s_add_u32 s26, s33, s6
	v_or_b32_e32 v4, v4, v1
	s_addc_u32 s27, s34, s7
	s_add_i32 s37, s36, 0
	v_lshlrev_b32_e32 v130, 1, v4
	v_mul_u32_u24_e32 v0, 0xb00, v0
	s_add_i32 m0, s37, 0x10000
	v_or_b32_e32 v0, v0, v1
	global_load_lds_dwordx4 v130, s[26:27]
	s_add_i32 m0, s37, 0x12000
	v_lshlrev_b32_e32 v134, 1, v0
	s_add_u32 s6, s26, 0xb0000
	global_load_lds_dwordx4 v134, s[26:27]
	s_addc_u32 s7, s27, 0
	s_add_i32 m0, s37, 0x14000
	s_mul_i32 s10, s51, 0x160000
	global_load_lds_dwordx4 v130, s[6:7]
	s_add_i32 m0, s37, 0x16000
	v_mul_u32_u24_e32 v11, 0xb00, v5
	s_mul_hi_i32 s8, s51, 0x160000
	s_add_u32 s24, s30, s10
	v_or_b32_e32 v5, v1, v11
	v_mul_u32_u24_e32 v12, 0xb00, v2
	s_addc_u32 s25, s31, s8
	s_add_i32 s38, s37, 0x2000
	v_lshlrev_b32_e32 v128, 1, v5
	v_or_b32_e32 v2, v12, v1
	global_load_lds_dwordx4 v134, s[6:7]
	s_mov_b32 m0, s37
	s_add_u32 s6, s24, 0xb0000
	v_lshlrev_b32_e32 v132, 1, v2
	global_load_lds_dwordx4 v128, s[24:25]
	s_mov_b32 m0, s38
	s_addc_u32 s7, s25, 0
	s_add_i32 s39, s37, 0x4000
	global_load_lds_dwordx4 v132, s[24:25]
	s_mov_b32 m0, s39
	s_add_i32 s40, s37, 0x6000
	global_load_lds_dwordx4 v128, s[6:7]
	s_mov_b32 m0, s40
	v_mov_b32_e32 v131, 0
	global_load_lds_dwordx4 v132, s[6:7]
	v_mov_b32_e32 v135, v131
	v_mov_b32_e32 v129, v131
	v_mov_b32_e32 v133, v131
	s_cmp_eq_u32 s1, 1
	s_mov_b32 s41, 0
	v_lshl_add_u64 v[6:7], s[26:27], 0, v[130:131]
	v_lshl_add_u64 v[4:5], s[26:27], 0, v[134:135]
	v_lshl_add_u64 v[0:1], s[24:25], 0, v[128:129]
	s_cselect_b64 s[6:7], -1, 0
	s_cmp_lg_u32 s1, 1
	v_lshl_add_u64 v[2:3], s[24:25], 0, v[132:133]
	s_cbranch_scc1 .LBB0_324
	s_barrier

.LBB0_463:
	s_cmp_lt_i32 s86, 5
	s_cselect_b64 s[2:3], -1, 0
	s_and_b64 s[2:3], s[2:3], s[0:1]
	s_andn2_b64 vcc, exec, s[2:3]
	s_cbranch_vccnz .LBB0_875
	s_bfe_u32 s0, s81, 0x20006
	s_cmp_eq_u32 s0, 0
	s_cbranch_scc1 .Lstg4_done

.Lstg4_done:
	s_cmpk_lt_i32 s81, 0x1700
	s_cselect_b64 s[8:9], -1, 0
	s_add_i32 s0, 0, 0x27e88
	v_mov_b32_e32 v0, s0
	ds_read2_b64 v[0:3], v0 offset1:1
	s_ashr_i32 s33, s81, 31
	s_cmpk_gt_i32 s81, 0x16ff
	v_readfirstlane_b32 s34, v182
	s_waitcnt lgkmcnt(0)
	v_readfirstlane_b32 s4, v0
	v_readfirstlane_b32 s5, v1
	v_readfirstlane_b32 s6, v2
	v_readfirstlane_b32 s7, v3
	s_cbranch_scc1 .LBB0_466
	s_ashr_i32 s0, s81, 31
	s_lshr_b32 s0, s0, 29
	s_add_i32 s0, s81, s0
	s_ashr_i32 s1, s0, 3
	s_and_b32 s0, s0, -8
	s_sub_i32 s0, s81, s0
	s_cmp_lt_i32 s0, 0
	s_movk_i32 s10, 0x2e1
	s_cselect_b32 s10, s10, 0x2e0
	s_mul_i32 s0, s0, s10
	s_add_i32 s0, s0, s1
	s_mul_hi_i32 s1, s0, 0xb21642c9
	s_add_i32 s1, s1, s0
	s_lshr_b32 s10, s1, 31
	s_ashr_i32 s1, s1, 7
	s_add_i32 s1, s1, s10
	s_lshl_b32 s10, s1, 3
	s_mulk_i32 s1, 0xb8
	s_sub_i32 s0, s0, s1
	s_bfe_u32 s1, s0, 0x3001c
	s_add_i32 s1, s0, s1
	s_sext_i32_i16 s11, s1
	s_and_b32 s1, s1, 0xfff8
	s_sub_i32 s0, s0, s1
	s_sext_i32_i16 s0, s0
	s_add_i32 s44, s10, s0
	s_ashr_i32 s0, s11, 3

.LBB0_1258:
	s_cmp_lt_i32 s86, 9
	s_cselect_b64 s[2:3], -1, 0
	s_and_b64 s[2:3], s[2:3], s[0:1]
	s_andn2_b64 vcc, exec, s[2:3]
	s_cbranch_vccnz .LBB0_1281
	s_bfe_u32 s0, s81, 0x20006
	s_cmp_eq_u32 s0, 0
	s_cbranch_scc1 .Lstg8_done

.Lstg8_done:
	s_cmpk_gt_i32 s81, 0x3ff
	v_readfirstlane_b32 s1, v182
	s_cbranch_scc1 .LBB0_1281
	s_waitcnt vmcnt(0)
	v_lshrrev_b32_e32 v4, 1, v182
	v_and_b32_e32 v10, 24, v4
	v_lshrrev_b32_e32 v4, 5, v182
	v_and_b32_e32 v4, 4, v4
	v_bfe_u32 v5, v182, 2, 2
	s_add_u32 s33, s84, 0x14000000
	v_lshlrev_b32_e32 v0, 4, v182
	v_and_b32_e32 v1, 32, v182
	v_bfe_u32 v2, v182, 2, 4
	v_or3_b32 v4, v4, v5, v10
	v_lshrrev_b32_e32 v5, 3, v182
	s_movk_i32 s0, 0x70
	s_addc_u32 s34, s85, 0
	v_bitop3_b32 v8, v0, v1, 48 bitop3:0x6c
	v_and_or_b32 v6, v5, s0, v2
	s_movk_i32 s0, 0x60
	v_add_u32_e32 v0, 0x2000, v0
	s_add_u32 s35, s84, 0x2700000
	v_and_or_b32 v5, v5, s0, v4
	v_lshrrev_b32_e32 v0, 7, v0
	s_movk_i32 s0, 0xf0
	s_addc_u32 s36, s85, 0
	v_and_or_b32 v2, v0, s0, v2
	s_movk_i32 s0, 0xe0
	s_ashr_i32 s37, s81, 31
	v_and_or_b32 v0, v0, s0, v4
	s_lshr_b32 s0, s37, 29
	s_add_i32 s0, s81, s0
	s_ashr_i32 s6, s0, 3
	s_and_b32 s0, s0, -8
	s_lshr_b32 s5, s1, 6
	s_sub_i32 s0, s81, s0
	s_lshr_b32 s4, s1, 8
	s_lshl_b32 s38, s5, 10
	s_lshl_b32 s8, s0, 7
	s_mul_i32 s7, s0, 0x81
	s_cmp_lt_i32 s0, 0
	s_cselect_b32 s0, s7, s8
	s_add_i32 s0, s0, s6
	s_ashr_i32 s6, s0, 31
	s_lshr_b32 s6, s6, 27
	s_add_i32 s6, s0, s6
	s_ashr_i32 s7, s6, 5
	s_and_b32 s6, s6, 0xffe0
	s_sub_i32 s6, s0, s6
	s_bfe_i32 s0, s6, 0x80000
	s_bfe_u32 s0, s0, 0x3000c
	s_add_i32 s8, s6, s0
	s_bfe_i32 s0, s8, 0x80000
	s_and_b32 s8, s8, 0xf8
	s_sext_i32_i16 s0, s0
	s_sub_i32 s6, s6, s8
	s_lshl_b32 s7, s7, 3
	s_lshr_b32 s0, s0, 3
	s_sext_i32_i8 s6, s6
	s_add_i32 s53, s7, s6
	s_bfe_i64 s[6:7], s[0:1], 0x100000
	s_lshl_b64 s[6:7], s[6:7], 20
	v_and_b32_e32 v9, 64, v182
	s_add_u32 s28, s35, s6
	v_or_b32_e32 v1, v8, v9
	s_addc_u32 s29, s36, s7
	s_add_i32 s39, s38, 0
	v_lshl_or_b32 v130, v5, 12, v1
	s_add_i32 m0, s39, 0x10000
	v_lshl_or_b32 v134, v0, 12, v1
	global_load_lds_dwordx4 v130, s[28:29]
	s_add_i32 m0, s39, 0x12000
	s_add_u32 s6, s28, 0x80000
	global_load_lds_dwordx4 v134, s[28:29]
	s_addc_u32 s7, s29, 0
	s_add_i32 m0, s39, 0x14000
	s_mul_i32 s9, s53, 0x2c0000
	global_load_lds_dwordx4 v130, s[6:7]
	s_add_i32 m0, s39, 0x16000
	v_lshrrev_b32_e32 v3, 1, v1
	v_mul_u32_u24_e32 v11, 0x1600, v6
	s_mul_hi_i32 s8, s53, 0x2c0000
	s_add_u32 s30, s33, s9
	v_or_b32_e32 v6, v3, v11
	v_mul_u32_u24_e32 v12, 0x1600, v2
	s_addc_u32 s31, s34, s8
	s_add_i32 s40, s39, 0x2000
	v_lshlrev_b32_e32 v128, 1, v6
	v_or_b32_e32 v2, v12, v3
	global_load_lds_dwordx4 v134, s[6:7]
	s_mov_b32 m0, s39
	s_add_u32 s6, s30, 0x160000
	v_lshlrev_b32_e32 v132, 1, v2
	global_load_lds_dwordx4 v128, s[30:31]
	s_mov_b32 m0, s40
	s_addc_u32 s7, s31, 0
	s_add_i32 s41, s39, 0x4000
	global_load_lds_dwordx4 v132, s[30:31]
	s_mov_b32 m0, s41
	s_add_i32 s42, s39, 0x6000
	global_load_lds_dwordx4 v128, s[6:7]
	s_mov_b32 m0, s42
	v_mov_b32_e32 v131, 0
	global_load_lds_dwordx4 v132, s[6:7]
	v_mov_b32_e32 v135, v131
	v_mov_b32_e32 v129, v131
	v_mov_b32_e32 v133, v131
	s_cmp_eq_u32 s4, 1
	s_mov_b32 s43, 0
	v_lshl_add_u64 v[6:7], s[28:29], 0, v[130:131]
	v_lshl_add_u64 v[4:5], s[28:29], 0, v[134:135]
	v_lshl_add_u64 v[0:1], s[30:31], 0, v[128:129]
	s_cselect_b64 s[6:7], -1, 0
	s_cmp_lg_u32 s4, 1
	v_lshl_add_u64 v[2:3], s[30:31], 0, v[132:133]
	s_cbranch_scc1 .LBB0_1262
	s_barrier

.LBB0_1399:
	s_cmp_lt_i32 s86, 11
	s_cselect_b64 s[2:3], -1, 0
	s_and_b64 s[2:3], s[2:3], s[0:1]
	s_andn2_b64 vcc, exec, s[2:3]
	s_cbranch_vccnz .LBB0_1416
	s_bfe_u32 s0, s81, 0x20006
	s_cmp_eq_u32 s0, 0
	s_cbranch_scc1 .Lstg10_done

.Lstg10_done:
	s_cmpk_gt_i32 s81, 0x15ff
	v_readfirstlane_b32 s1, v182
	s_cbranch_scc1 .LBB0_1416
	v_lshrrev_b32_e32 v2, 1, v182
	s_waitcnt vmcnt(0)
	v_and_b32_e32 v11, 24, v2
	v_lshrrev_b32_e32 v2, 5, v182
	v_and_b32_e32 v2, 4, v2
	v_bfe_u32 v3, v182, 2, 2
	s_add_u32 s28, s84, 0x2a000000
	v_lshlrev_b32_e32 v0, 4, v182
	v_and_b32_e32 v1, 32, v182
	v_bfe_u32 v10, v182, 2, 4
	v_or3_b32 v2, v2, v3, v11
	v_lshrrev_b32_e32 v3, 3, v182
	s_movk_i32 s0, 0x70
	s_addc_u32 s29, s85, 0
	v_bitop3_b32 v8, v0, v1, 48 bitop3:0x6c
	v_and_b32_e32 v9, 64, v182
	v_and_or_b32 v4, v3, s0, v10
	s_movk_i32 s0, 0x60
	v_add_u32_e32 v12, 0x2000, v0
	s_add_u32 s30, s84, 0x2b00000
	v_or_b32_e32 v1, v8, v9
	v_and_or_b32 v3, v3, s0, v2
	v_lshrrev_b32_e32 v0, 7, v12
	s_movk_i32 s0, 0xf0
	s_addc_u32 s31, s85, 0
	v_lshl_or_b32 v130, v3, 11, v1
	v_and_or_b32 v3, v0, s0, v10
	s_movk_i32 s0, 0xe0
	s_ashr_i32 s33, s81, 31
	v_and_or_b32 v0, v0, s0, v2
	s_lshr_b32 s0, s33, 29
	s_add_i32 s0, s81, s0
	s_lshr_b32 s8, s1, 6
	s_ashr_i32 s4, s0, 3
	s_and_b32 s0, s0, -8
	s_lshr_b32 s10, s1, 8
	s_lshl_b32 s34, s8, 10
	s_sub_i32 s0, s81, s0
	s_cmp_lt_i32 s0, 0
	s_movk_i32 s35, 0x2c1
	s_cselect_b32 s5, s35, 0x2c0
	s_mul_i32 s0, s0, s5
	s_add_i32 s0, s0, s4
	s_mul_hi_i32 s4, s0, 0x2e8ba2e9
	s_lshr_b32 s5, s4, 31
	s_ashr_i32 s4, s4, 5
	s_add_i32 s4, s4, s5
	s_lshl_b32 s5, s4, 3
	s_mulk_i32 s4, 0xb0
	s_sub_i32 s4, s0, s4
	s_bfe_u32 s0, s4, 0x3001c
	s_add_i32 s6, s4, s0
	s_sext_i32_i16 s0, s6
	s_and_b32 s6, s6, 0xfff8
	s_sub_i32 s4, s4, s6
	s_sext_i32_i16 s4, s4
	s_lshr_b32 s0, s0, 3
	s_add_i32 s20, s5, s4
	s_ashr_i32 s21, s20, 31
	s_bfe_i64 s[6:7], s[0:1], 0x100000
	s_lshl_b64 s[4:5], s[20:21], 19
	s_lshl_b64 s[6:7], s[6:7], 19
	s_add_u32 s24, s30, s6
	s_addc_u32 s25, s31, s7
	s_add_i32 s21, s34, 0
	s_add_i32 m0, s21, 0x10000
	v_lshl_or_b32 v134, v0, 11, v1
	global_load_lds_dwordx4 v130, s[24:25]
	s_add_i32 m0, s21, 0x12000
	s_add_u32 s6, s24, 0x40000
	global_load_lds_dwordx4 v134, s[24:25]
	s_addc_u32 s7, s25, 0
	s_add_i32 m0, s21, 0x14000
	v_lshl_or_b32 v128, v4, 11, v1
	global_load_lds_dwordx4 v130, s[6:7]
	s_add_i32 m0, s21, 0x16000
	s_add_u32 s22, s28, s4
	s_addc_u32 s23, s29, s5
	s_add_i32 s36, s21, 0x2000
	global_load_lds_dwordx4 v134, s[6:7]
	s_mov_b32 m0, s21
	s_add_u32 s4, s22, 0x40000
	v_lshl_or_b32 v132, v3, 11, v1
	global_load_lds_dwordx4 v128, s[22:23]
	s_mov_b32 m0, s36
	s_addc_u32 s5, s23, 0
	s_add_i32 s37, s21, 0x4000
	global_load_lds_dwordx4 v132, s[22:23]
	s_mov_b32 m0, s37
	s_add_i32 s38, s21, 0x6000
	global_load_lds_dwordx4 v128, s[4:5]
	s_mov_b32 m0, s38
	v_mov_b32_e32 v131, 0
	global_load_lds_dwordx4 v132, s[4:5]
	v_mov_b32_e32 v135, v131
	v_mov_b32_e32 v129, v131
	v_mov_b32_e32 v133, v131
	s_cmp_eq_u32 s10, 1
	s_mov_b32 s39, 0
	v_lshl_add_u64 v[6:7], s[24:25], 0, v[130:131]
	v_lshl_add_u64 v[4:5], s[24:25], 0, v[134:135]
	v_lshl_add_u64 v[0:1], s[22:23], 0, v[128:129]
	s_cselect_b64 s[4:5], -1, 0
	s_cmp_lg_u32 s10, 1
	v_lshl_add_u64 v[2:3], s[22:23], 0, v[132:133]
	s_cbranch_scc1 .LBB0_1403
	s_barrier

.LBB0_1470:
	s_cmp_lt_i32 s86, 12
	s_cselect_b64 s[2:3], -1, 0
	s_and_b64 s[2:3], s[2:3], s[0:1]
	s_andn2_b64 vcc, exec, s[2:3]
	s_cbranch_vccnz .LBB0_1495
	s_bfe_u32 s0, s81, 0x20006
	s_cmp_eq_u32 s0, 0
	s_cbranch_scc1 .Lstg11_done

.Lstg11_done:
	s_cmpk_gt_i32 s81, 0x3ff
	v_readfirstlane_b32 s0, v182
	s_cbranch_scc1 .LBB0_1495
	s_add_u32 s30, s84, 0x14000000
	s_addc_u32 s31, s85, 0
	v_lshrrev_b32_e32 v3, 1, v182
	s_add_u32 s33, s84, 0x3600000
	s_waitcnt vmcnt(0)
	v_and_b32_e32 v10, 24, v3
	v_lshrrev_b32_e32 v3, 5, v182
	s_addc_u32 s34, s85, 0
	v_and_b32_e32 v3, 4, v3
	v_bfe_u32 v4, v182, 2, 2
	s_ashr_i32 s35, s81, 31
	v_lshlrev_b32_e32 v0, 4, v182
	v_and_b32_e32 v1, 32, v182
	v_bfe_u32 v2, v182, 2, 4
	v_or3_b32 v3, v3, v4, v10
	v_lshrrev_b32_e32 v4, 3, v182
	s_movk_i32 s1, 0x70
	s_lshr_b32 s4, s35, 29
	v_bitop3_b32 v8, v0, v1, 48 bitop3:0x6c
	v_and_or_b32 v5, v4, s1, v2
	s_movk_i32 s1, 0x60
	v_add_u32_e32 v0, 0x2000, v0
	s_add_i32 s4, s81, s4
	v_and_or_b32 v4, v4, s1, v3
	v_lshrrev_b32_e32 v0, 7, v0
	s_movk_i32 s1, 0xf0
	s_ashr_i32 s6, s4, 3
	s_and_b32 s4, s4, -8
	v_and_or_b32 v2, v0, s1, v2
	s_movk_i32 s1, 0xe0
	s_lshr_b32 s5, s0, 6
	s_sub_i32 s4, s81, s4
	v_and_or_b32 v0, v0, s1, v3
	s_lshr_b32 s1, s0, 8
	s_lshl_b32 s36, s5, 10
	s_lshl_b32 s8, s4, 7
	s_mul_i32 s7, s4, 0x81
	s_cmp_lt_i32 s4, 0
	s_cselect_b32 s4, s7, s8
	s_add_i32 s4, s4, s6
	s_ashr_i32 s6, s4, 31
	s_lshr_b32 s6, s6, 27
	s_add_i32 s6, s4, s6
	s_ashr_i32 s7, s6, 5
	s_and_b32 s6, s6, 0xffe0
	s_sub_i32 s6, s4, s6
	s_bfe_i32 s4, s6, 0x80000
	s_bfe_u32 s4, s4, 0x3000c
	s_add_i32 s8, s6, s4
	s_bfe_i32 s4, s8, 0x80000
	s_and_b32 s8, s8, 0xf8
	s_sub_i32 s6, s6, s8
	s_lshl_b32 s7, s7, 3
	s_sext_i32_i16 s9, s4
	s_sext_i32_i8 s6, s6
	v_and_b32_e32 v9, 64, v182
	s_add_i32 s51, s7, s6
	s_ashr_i32 s6, s9, 3
	v_or_b32_e32 v1, v8, v9
	s_lshr_b32 s4, s9, 3
	s_mul_hi_i32 s7, s6, 0x160000
	s_mul_i32 s6, s6, 0x160000
	v_lshrrev_b32_e32 v1, 1, v1
	v_mul_u32_u24_e32 v4, 0xb00, v4
	s_add_u32 s26, s33, s6
	v_or_b32_e32 v4, v4, v1
	s_addc_u32 s27, s34, s7
	s_add_i32 s37, s36, 0
	v_lshlrev_b32_e32 v130, 1, v4
	v_mul_u32_u24_e32 v0, 0xb00, v0
	s_add_i32 m0, s37, 0x10000
	v_or_b32_e32 v0, v0, v1
	global_load_lds_dwordx4 v130, s[26:27]
	s_add_i32 m0, s37, 0x12000
	v_lshlrev_b32_e32 v134, 1, v0
	s_add_u32 s6, s26, 0xb0000
	global_load_lds_dwordx4 v134, s[26:27]
	s_addc_u32 s7, s27, 0
	s_add_i32 m0, s37, 0x14000
	s_mul_i32 s10, s51, 0x160000
	global_load_lds_dwordx4 v130, s[6:7]
	s_add_i32 m0, s37, 0x16000
	v_mul_u32_u24_e32 v11, 0xb00, v5
	s_mul_hi_i32 s8, s51, 0x160000
	s_add_u32 s24, s30, s10
	v_or_b32_e32 v5, v1, v11
	v_mul_u32_u24_e32 v12, 0xb00, v2
	s_addc_u32 s25, s31, s8
	s_add_i32 s38, s37, 0x2000
	v_lshlrev_b32_e32 v128, 1, v5
	v_or_b32_e32 v2, v12, v1
	global_load_lds_dwordx4 v134, s[6:7]
	s_mov_b32 m0, s37
	s_add_u32 s6, s24, 0xb0000
	v_lshlrev_b32_e32 v132, 1, v2
	global_load_lds_dwordx4 v128, s[24:25]
	s_mov_b32 m0, s38
	s_addc_u32 s7, s25, 0
	s_add_i32 s39, s37, 0x4000
	global_load_lds_dwordx4 v132, s[24:25]
	s_mov_b32 m0, s39
	s_add_i32 s40, s37, 0x6000
	global_load_lds_dwordx4 v128, s[6:7]
	s_mov_b32 m0, s40
	v_mov_b32_e32 v131, 0
	global_load_lds_dwordx4 v132, s[6:7]
	v_mov_b32_e32 v135, v131
	v_mov_b32_e32 v129, v131
	v_mov_b32_e32 v133, v131
	s_cmp_eq_u32 s1, 1
	s_mov_b32 s41, 0
	v_lshl_add_u64 v[6:7], s[26:27], 0, v[130:131]
	v_lshl_add_u64 v[4:5], s[26:27], 0, v[134:135]
	v_lshl_add_u64 v[0:1], s[24:25], 0, v[128:129]
	s_cselect_b64 s[6:7], -1, 0
	s_cmp_lg_u32 s1, 1
	v_lshl_add_u64 v[2:3], s[24:25], 0, v[132:133]
	s_cbranch_scc1 .LBB0_1474
	s_barrier
